# P11 silu epilogue hand-written with packed f32 math (g*u*r^2*rcp(1+exp2(-log2e*r*g))), 62 -> 29 VALU per row group, same transcendental count
# speedup vs baseline: 1.0104x; 1.0055x over previous
.LBB0_1307:
	s_lshl_b32 s20, s20, 7
	s_ashr_i32 s21, s20, 31
	s_lshl_b64 s[20:21], s[20:21], 1
	v_mov_b64_e32 v[150:151], s[66:67]
	v_mad_i64_i32 v[152:153], s[22:23], v148, s36, v[150:151]
	v_lshl_add_u64 v[152:153], v[152:153], 0, s[20:21]
	v_and_b32_e32 v150, 0xf0, v136
	v_mov_b32_e32 v151, 0
	v_lshl_add_u64 v[152:153], v[152:153], 0, v[150:151]
	s_mov_b32 s23, 0
	v_mul_f32_e32 v154, 0xbfb8aa3b, v236
	v_mul_f32_e32 v156, v236, v236
	v_pk_mul_f32 v[158:159], v[116:117], v[154:155] op_sel_hi:[1,0]
	v_pk_mul_f32 v[160:161], v[118:119], v[154:155] op_sel_hi:[1,0]
	v_pk_mul_f32 v[162:163], v[112:113], v[154:155] op_sel_hi:[1,0]
	v_pk_mul_f32 v[164:165], v[114:115], v[154:155] op_sel_hi:[1,0]
	v_exp_f32_e32 v158, v158
	v_exp_f32_e32 v159, v159
	v_exp_f32_e32 v160, v160
	v_exp_f32_e32 v161, v161
	v_exp_f32_e32 v162, v162
	v_exp_f32_e32 v163, v163
	v_exp_f32_e32 v164, v164
	v_exp_f32_e32 v165, v165
	v_pk_mul_f32 v[124:125], v[116:117], v[124:125]
	v_pk_mul_f32 v[126:127], v[118:119], v[126:127]
	v_pk_mul_f32 v[120:121], v[112:113], v[120:121]
	v_pk_mul_f32 v[122:123], v[114:115], v[122:123]
	v_pk_add_f32 v[158:159], v[158:159], 1.0 op_sel_hi:[1,0]
	v_pk_add_f32 v[160:161], v[160:161], 1.0 op_sel_hi:[1,0]
	v_pk_add_f32 v[162:163], v[162:163], 1.0 op_sel_hi:[1,0]
	v_pk_add_f32 v[164:165], v[164:165], 1.0 op_sel_hi:[1,0]
	v_rcp_f32_e32 v158, v158
	v_rcp_f32_e32 v159, v159
	v_rcp_f32_e32 v160, v160
	v_rcp_f32_e32 v161, v161
	v_rcp_f32_e32 v162, v162
	v_rcp_f32_e32 v163, v163
	v_rcp_f32_e32 v164, v164
	v_rcp_f32_e32 v165, v165
	v_pk_mul_f32 v[124:125], v[124:125], v[156:157] op_sel_hi:[1,0]
	v_pk_mul_f32 v[126:127], v[126:127], v[156:157] op_sel_hi:[1,0]
	v_pk_mul_f32 v[120:121], v[120:121], v[156:157] op_sel_hi:[1,0]
	v_pk_mul_f32 v[122:123], v[122:123], v[156:157] op_sel_hi:[1,0]
	v_pk_mul_f32 v[124:125], v[124:125], v[158:159]
	v_pk_mul_f32 v[126:127], v[126:127], v[160:161]
	v_pk_mul_f32 v[120:121], v[120:121], v[162:163]
	v_pk_mul_f32 v[122:123], v[122:123], v[164:165]
	v_cvt_pk_bf16_f32 v116, v124, v125
	v_cvt_pk_bf16_f32 v117, v126, v127
	v_cvt_pk_bf16_f32 v118, v120, v121
	v_cvt_pk_bf16_f32 v119, v122, v123
	global_store_dwordx4 v[152:153], v[116:119], off
	v_mul_f32_e32 v154, 0xbfb8aa3b, v237
	v_mul_f32_e32 v156, v237, v237
	v_pk_mul_f32 v[158:159], v[100:101], v[154:155] op_sel_hi:[1,0]
	v_pk_mul_f32 v[160:161], v[102:103], v[154:155] op_sel_hi:[1,0]
	v_pk_mul_f32 v[162:163], v[96:97], v[154:155] op_sel_hi:[1,0]
	v_pk_mul_f32 v[164:165], v[98:99], v[154:155] op_sel_hi:[1,0]
	v_exp_f32_e32 v158, v158
	v_exp_f32_e32 v159, v159
	v_exp_f32_e32 v160, v160
	v_exp_f32_e32 v161, v161
	v_exp_f32_e32 v162, v162
	v_exp_f32_e32 v163, v163
	v_exp_f32_e32 v164, v164
	v_exp_f32_e32 v165, v165
	v_pk_mul_f32 v[108:109], v[100:101], v[108:109]
	v_pk_mul_f32 v[110:111], v[102:103], v[110:111]
	v_pk_mul_f32 v[104:105], v[96:97], v[104:105]
	v_pk_mul_f32 v[106:107], v[98:99], v[106:107]
	v_pk_add_f32 v[158:159], v[158:159], 1.0 op_sel_hi:[1,0]
	v_pk_add_f32 v[160:161], v[160:161], 1.0 op_sel_hi:[1,0]
	v_pk_add_f32 v[162:163], v[162:163], 1.0 op_sel_hi:[1,0]
	v_pk_add_f32 v[164:165], v[164:165], 1.0 op_sel_hi:[1,0]
	v_rcp_f32_e32 v158, v158
	v_rcp_f32_e32 v159, v159
	v_rcp_f32_e32 v160, v160
	v_rcp_f32_e32 v161, v161
	v_rcp_f32_e32 v162, v162
	v_rcp_f32_e32 v163, v163
	v_rcp_f32_e32 v164, v164
	v_rcp_f32_e32 v165, v165
	v_pk_mul_f32 v[108:109], v[108:109], v[156:157] op_sel_hi:[1,0]
	v_pk_mul_f32 v[110:111], v[110:111], v[156:157] op_sel_hi:[1,0]
	v_pk_mul_f32 v[104:105], v[104:105], v[156:157] op_sel_hi:[1,0]
	v_pk_mul_f32 v[106:107], v[106:107], v[156:157] op_sel_hi:[1,0]
	v_pk_mul_f32 v[108:109], v[108:109], v[158:159]
	v_pk_mul_f32 v[110:111], v[110:111], v[160:161]
	v_pk_mul_f32 v[104:105], v[104:105], v[162:163]
	v_pk_mul_f32 v[106:107], v[106:107], v[164:165]
	v_cvt_pk_bf16_f32 v100, v108, v109
	v_cvt_pk_bf16_f32 v101, v110, v111
	v_cvt_pk_bf16_f32 v102, v104, v105
	v_cvt_pk_bf16_f32 v103, v106, v107
	s_mov_b32 s22, 0x16000
	v_lshl_add_u64 v[96:97], v[152:153], 0, s[22:23]
	global_store_dwordx4 v[96:97], v[100:103], off
	v_mul_f32_e32 v154, 0xbfb8aa3b, v238
	v_mul_f32_e32 v156, v238, v238
	v_pk_mul_f32 v[158:159], v[84:85], v[154:155] op_sel_hi:[1,0]
	v_pk_mul_f32 v[160:161], v[86:87], v[154:155] op_sel_hi:[1,0]
	v_pk_mul_f32 v[162:163], v[80:81], v[154:155] op_sel_hi:[1,0]
	v_pk_mul_f32 v[164:165], v[82:83], v[154:155] op_sel_hi:[1,0]
	v_exp_f32_e32 v158, v158
	v_exp_f32_e32 v159, v159
	v_exp_f32_e32 v160, v160
	v_exp_f32_e32 v161, v161
	v_exp_f32_e32 v162, v162
	v_exp_f32_e32 v163, v163
	v_exp_f32_e32 v164, v164
	v_exp_f32_e32 v165, v165
	v_pk_mul_f32 v[92:93], v[84:85], v[92:93]
	v_pk_mul_f32 v[94:95], v[86:87], v[94:95]
	v_pk_mul_f32 v[88:89], v[80:81], v[88:89]
	v_pk_mul_f32 v[90:91], v[82:83], v[90:91]
	v_pk_add_f32 v[158:159], v[158:159], 1.0 op_sel_hi:[1,0]
	v_pk_add_f32 v[160:161], v[160:161], 1.0 op_sel_hi:[1,0]
	v_pk_add_f32 v[162:163], v[162:163], 1.0 op_sel_hi:[1,0]
	v_pk_add_f32 v[164:165], v[164:165], 1.0 op_sel_hi:[1,0]
	v_rcp_f32_e32 v158, v158
	v_rcp_f32_e32 v159, v159
	v_rcp_f32_e32 v160, v160
	v_rcp_f32_e32 v161, v161
	v_rcp_f32_e32 v162, v162
	v_rcp_f32_e32 v163, v163
	v_rcp_f32_e32 v164, v164
	v_rcp_f32_e32 v165, v165
	v_pk_mul_f32 v[92:93], v[92:93], v[156:157] op_sel_hi:[1,0]
	v_pk_mul_f32 v[94:95], v[94:95], v[156:157] op_sel_hi:[1,0]
	v_pk_mul_f32 v[88:89], v[88:89], v[156:157] op_sel_hi:[1,0]
	v_pk_mul_f32 v[90:91], v[90:91], v[156:157] op_sel_hi:[1,0]
	v_pk_mul_f32 v[92:93], v[92:93], v[158:159]
	v_pk_mul_f32 v[94:95], v[94:95], v[160:161]
	v_pk_mul_f32 v[88:89], v[88:89], v[162:163]
	v_pk_mul_f32 v[90:91], v[90:91], v[164:165]
	v_cvt_pk_bf16_f32 v84, v92, v93
	v_cvt_pk_bf16_f32 v85, v94, v95
	v_cvt_pk_bf16_f32 v86, v88, v89
	v_cvt_pk_bf16_f32 v87, v90, v91
	s_mov_b32 s22, 0x2c000
	v_lshl_add_u64 v[80:81], v[152:153], 0, s[22:23]
	global_store_dwordx4 v[80:81], v[84:87], off
	v_mul_f32_e32 v154, 0xbfb8aa3b, v239
	v_mul_f32_e32 v156, v239, v239
	v_pk_mul_f32 v[158:159], v[68:69], v[154:155] op_sel_hi:[1,0]
	v_pk_mul_f32 v[160:161], v[70:71], v[154:155] op_sel_hi:[1,0]
	v_pk_mul_f32 v[162:163], v[64:65], v[154:155] op_sel_hi:[1,0]
	v_pk_mul_f32 v[164:165], v[66:67], v[154:155] op_sel_hi:[1,0]
	v_exp_f32_e32 v158, v158
	v_exp_f32_e32 v159, v159
	v_exp_f32_e32 v160, v160
	v_exp_f32_e32 v161, v161
	v_exp_f32_e32 v162, v162
	v_exp_f32_e32 v163, v163
	v_exp_f32_e32 v164, v164
	v_exp_f32_e32 v165, v165
	v_pk_mul_f32 v[76:77], v[68:69], v[76:77]
	v_pk_mul_f32 v[78:79], v[70:71], v[78:79]
	v_pk_mul_f32 v[72:73], v[64:65], v[72:73]
	v_pk_mul_f32 v[74:75], v[66:67], v[74:75]
	v_pk_add_f32 v[158:159], v[158:159], 1.0 op_sel_hi:[1,0]
	v_pk_add_f32 v[160:161], v[160:161], 1.0 op_sel_hi:[1,0]
	v_pk_add_f32 v[162:163], v[162:163], 1.0 op_sel_hi:[1,0]
	v_pk_add_f32 v[164:165], v[164:165], 1.0 op_sel_hi:[1,0]
	v_rcp_f32_e32 v158, v158
	v_rcp_f32_e32 v159, v159
	v_rcp_f32_e32 v160, v160
	v_rcp_f32_e32 v161, v161
	v_rcp_f32_e32 v162, v162
	v_rcp_f32_e32 v163, v163
	v_rcp_f32_e32 v164, v164
	v_rcp_f32_e32 v165, v165
	v_pk_mul_f32 v[76:77], v[76:77], v[156:157] op_sel_hi:[1,0]
	v_pk_mul_f32 v[78:79], v[78:79], v[156:157] op_sel_hi:[1,0]
	v_pk_mul_f32 v[72:73], v[72:73], v[156:157] op_sel_hi:[1,0]
	v_pk_mul_f32 v[74:75], v[74:75], v[156:157] op_sel_hi:[1,0]
	v_pk_mul_f32 v[76:77], v[76:77], v[158:159]
	v_pk_mul_f32 v[78:79], v[78:79], v[160:161]
	v_pk_mul_f32 v[72:73], v[72:73], v[162:163]
	v_pk_mul_f32 v[74:75], v[74:75], v[164:165]
	v_cvt_pk_bf16_f32 v68, v76, v77
	v_cvt_pk_bf16_f32 v69, v78, v79
	v_cvt_pk_bf16_f32 v70, v72, v73
	v_cvt_pk_bf16_f32 v71, v74, v75
	s_mov_b32 s22, 0x42000
	v_lshl_add_u64 v[64:65], v[152:153], 0, s[22:23]
	global_store_dwordx4 v[64:65], v[68:71], off
	v_mul_f32_e32 v154, 0xbfb8aa3b, v240
	v_mul_f32_e32 v156, v240, v240
	v_pk_mul_f32 v[158:159], v[52:53], v[154:155] op_sel_hi:[1,0]
	v_pk_mul_f32 v[160:161], v[54:55], v[154:155] op_sel_hi:[1,0]
	v_pk_mul_f32 v[162:163], v[48:49], v[154:155] op_sel_hi:[1,0]
	v_pk_mul_f32 v[164:165], v[50:51], v[154:155] op_sel_hi:[1,0]
	v_exp_f32_e32 v158, v158
	v_exp_f32_e32 v159, v159
	v_exp_f32_e32 v160, v160
	v_exp_f32_e32 v161, v161
	v_exp_f32_e32 v162, v162
	v_exp_f32_e32 v163, v163
	v_exp_f32_e32 v164, v164
	v_exp_f32_e32 v165, v165
	v_pk_mul_f32 v[60:61], v[52:53], v[60:61]
	v_pk_mul_f32 v[62:63], v[54:55], v[62:63]
	v_pk_mul_f32 v[56:57], v[48:49], v[56:57]
	v_pk_mul_f32 v[58:59], v[50:51], v[58:59]
	v_pk_add_f32 v[158:159], v[158:159], 1.0 op_sel_hi:[1,0]
	v_pk_add_f32 v[160:161], v[160:161], 1.0 op_sel_hi:[1,0]
	v_pk_add_f32 v[162:163], v[162:163], 1.0 op_sel_hi:[1,0]
	v_pk_add_f32 v[164:165], v[164:165], 1.0 op_sel_hi:[1,0]
	v_rcp_f32_e32 v158, v158
	v_rcp_f32_e32 v159, v159
	v_rcp_f32_e32 v160, v160
	v_rcp_f32_e32 v161, v161
	v_rcp_f32_e32 v162, v162
	v_rcp_f32_e32 v163, v163
	v_rcp_f32_e32 v164, v164
	v_rcp_f32_e32 v165, v165
	v_pk_mul_f32 v[60:61], v[60:61], v[156:157] op_sel_hi:[1,0]
	v_pk_mul_f32 v[62:63], v[62:63], v[156:157] op_sel_hi:[1,0]
	v_pk_mul_f32 v[56:57], v[56:57], v[156:157] op_sel_hi:[1,0]
	v_pk_mul_f32 v[58:59], v[58:59], v[156:157] op_sel_hi:[1,0]
	v_pk_mul_f32 v[60:61], v[60:61], v[158:159]
	v_pk_mul_f32 v[62:63], v[62:63], v[160:161]
	v_pk_mul_f32 v[56:57], v[56:57], v[162:163]
	v_pk_mul_f32 v[58:59], v[58:59], v[164:165]
	v_cvt_pk_bf16_f32 v52, v60, v61
	v_cvt_pk_bf16_f32 v53, v62, v63
	v_cvt_pk_bf16_f32 v54, v56, v57
	v_cvt_pk_bf16_f32 v55, v58, v59
	s_mov_b32 s22, 0xb0000
	v_lshl_add_u64 v[48:49], v[152:153], 0, s[22:23]
	global_store_dwordx4 v[48:49], v[52:55], off
	v_mul_f32_e32 v154, 0xbfb8aa3b, v241
	v_mul_f32_e32 v156, v241, v241
	v_pk_mul_f32 v[158:159], v[36:37], v[154:155] op_sel_hi:[1,0]
	v_pk_mul_f32 v[160:161], v[38:39], v[154:155] op_sel_hi:[1,0]
	v_pk_mul_f32 v[162:163], v[32:33], v[154:155] op_sel_hi:[1,0]
	v_pk_mul_f32 v[164:165], v[34:35], v[154:155] op_sel_hi:[1,0]
	v_exp_f32_e32 v158, v158
	v_exp_f32_e32 v159, v159
	v_exp_f32_e32 v160, v160
	v_exp_f32_e32 v161, v161
	v_exp_f32_e32 v162, v162
	v_exp_f32_e32 v163, v163
	v_exp_f32_e32 v164, v164
	v_exp_f32_e32 v165, v165
	v_pk_mul_f32 v[44:45], v[36:37], v[44:45]
	v_pk_mul_f32 v[46:47], v[38:39], v[46:47]
	v_pk_mul_f32 v[40:41], v[32:33], v[40:41]
	v_pk_mul_f32 v[42:43], v[34:35], v[42:43]
	v_pk_add_f32 v[158:159], v[158:159], 1.0 op_sel_hi:[1,0]
	v_pk_add_f32 v[160:161], v[160:161], 1.0 op_sel_hi:[1,0]
	v_pk_add_f32 v[162:163], v[162:163], 1.0 op_sel_hi:[1,0]
	v_pk_add_f32 v[164:165], v[164:165], 1.0 op_sel_hi:[1,0]
	v_rcp_f32_e32 v158, v158
	v_rcp_f32_e32 v159, v159
	v_rcp_f32_e32 v160, v160
	v_rcp_f32_e32 v161, v161
	v_rcp_f32_e32 v162, v162
	v_rcp_f32_e32 v163, v163
	v_rcp_f32_e32 v164, v164
	v_rcp_f32_e32 v165, v165
	v_pk_mul_f32 v[44:45], v[44:45], v[156:157] op_sel_hi:[1,0]
	v_pk_mul_f32 v[46:47], v[46:47], v[156:157] op_sel_hi:[1,0]
	v_pk_mul_f32 v[40:41], v[40:41], v[156:157] op_sel_hi:[1,0]
	v_pk_mul_f32 v[42:43], v[42:43], v[156:157] op_sel_hi:[1,0]
	v_pk_mul_f32 v[44:45], v[44:45], v[158:159]
	v_pk_mul_f32 v[46:47], v[46:47], v[160:161]
	v_pk_mul_f32 v[40:41], v[40:41], v[162:163]
	v_pk_mul_f32 v[42:43], v[42:43], v[164:165]
	v_cvt_pk_bf16_f32 v36, v44, v45
	v_cvt_pk_bf16_f32 v37, v46, v47
	v_cvt_pk_bf16_f32 v38, v40, v41
	v_cvt_pk_bf16_f32 v39, v42, v43
	s_mov_b32 s22, 0xc6000
	v_lshl_add_u64 v[32:33], v[152:153], 0, s[22:23]
	global_store_dwordx4 v[32:33], v[36:39], off
	v_mul_f32_e32 v154, 0xbfb8aa3b, v242
	v_mul_f32_e32 v156, v242, v242
	v_pk_mul_f32 v[158:159], v[20:21], v[154:155] op_sel_hi:[1,0]
	v_pk_mul_f32 v[160:161], v[22:23], v[154:155] op_sel_hi:[1,0]
	v_pk_mul_f32 v[162:163], v[16:17], v[154:155] op_sel_hi:[1,0]
	v_pk_mul_f32 v[164:165], v[18:19], v[154:155] op_sel_hi:[1,0]
	v_exp_f32_e32 v158, v158
	v_exp_f32_e32 v159, v159
	v_exp_f32_e32 v160, v160
	v_exp_f32_e32 v161, v161
	v_exp_f32_e32 v162, v162
	v_exp_f32_e32 v163, v163
	v_exp_f32_e32 v164, v164
	v_exp_f32_e32 v165, v165
	v_pk_mul_f32 v[28:29], v[20:21], v[28:29]
	v_pk_mul_f32 v[30:31], v[22:23], v[30:31]
	v_pk_mul_f32 v[24:25], v[16:17], v[24:25]
	v_pk_mul_f32 v[26:27], v[18:19], v[26:27]
	v_pk_add_f32 v[158:159], v[158:159], 1.0 op_sel_hi:[1,0]
	v_pk_add_f32 v[160:161], v[160:161], 1.0 op_sel_hi:[1,0]
	v_pk_add_f32 v[162:163], v[162:163], 1.0 op_sel_hi:[1,0]
	v_pk_add_f32 v[164:165], v[164:165], 1.0 op_sel_hi:[1,0]
	v_rcp_f32_e32 v158, v158
	v_rcp_f32_e32 v159, v159
	v_rcp_f32_e32 v160, v160
	v_rcp_f32_e32 v161, v161
	v_rcp_f32_e32 v162, v162
	v_rcp_f32_e32 v163, v163
	v_rcp_f32_e32 v164, v164
	v_rcp_f32_e32 v165, v165
	v_pk_mul_f32 v[28:29], v[28:29], v[156:157] op_sel_hi:[1,0]
	v_pk_mul_f32 v[30:31], v[30:31], v[156:157] op_sel_hi:[1,0]
	v_pk_mul_f32 v[24:25], v[24:25], v[156:157] op_sel_hi:[1,0]
	v_pk_mul_f32 v[26:27], v[26:27], v[156:157] op_sel_hi:[1,0]
	v_pk_mul_f32 v[28:29], v[28:29], v[158:159]
	v_pk_mul_f32 v[30:31], v[30:31], v[160:161]
	v_pk_mul_f32 v[24:25], v[24:25], v[162:163]
	v_pk_mul_f32 v[26:27], v[26:27], v[164:165]
	v_cvt_pk_bf16_f32 v20, v28, v29
	v_cvt_pk_bf16_f32 v21, v30, v31
	v_cvt_pk_bf16_f32 v22, v24, v25
	v_cvt_pk_bf16_f32 v23, v26, v27
	s_mov_b32 s22, 0xdc000
	v_lshl_add_u64 v[16:17], v[152:153], 0, s[22:23]
	global_store_dwordx4 v[16:17], v[20:23], off
	v_mul_f32_e32 v154, 0xbfb8aa3b, v243
	v_mul_f32_e32 v156, v243, v243
	v_pk_mul_f32 v[158:159], v[4:5], v[154:155] op_sel_hi:[1,0]
	v_pk_mul_f32 v[160:161], v[6:7], v[154:155] op_sel_hi:[1,0]
	v_pk_mul_f32 v[162:163], v[0:1], v[154:155] op_sel_hi:[1,0]
	v_pk_mul_f32 v[164:165], v[2:3], v[154:155] op_sel_hi:[1,0]
	v_exp_f32_e32 v158, v158
	v_exp_f32_e32 v159, v159
	v_exp_f32_e32 v160, v160
	v_exp_f32_e32 v161, v161
	v_exp_f32_e32 v162, v162
	v_exp_f32_e32 v163, v163
	v_exp_f32_e32 v164, v164
	v_exp_f32_e32 v165, v165
	v_pk_mul_f32 v[12:13], v[4:5], v[12:13]
	v_pk_mul_f32 v[14:15], v[6:7], v[14:15]
	v_pk_mul_f32 v[8:9], v[0:1], v[8:9]
	v_pk_mul_f32 v[10:11], v[2:3], v[10:11]
	v_pk_add_f32 v[158:159], v[158:159], 1.0 op_sel_hi:[1,0]
	v_pk_add_f32 v[160:161], v[160:161], 1.0 op_sel_hi:[1,0]
	v_pk_add_f32 v[162:163], v[162:163], 1.0 op_sel_hi:[1,0]
	v_pk_add_f32 v[164:165], v[164:165], 1.0 op_sel_hi:[1,0]
	v_rcp_f32_e32 v158, v158
	v_rcp_f32_e32 v159, v159
	v_rcp_f32_e32 v160, v160
	v_rcp_f32_e32 v161, v161
	v_rcp_f32_e32 v162, v162
	v_rcp_f32_e32 v163, v163
	v_rcp_f32_e32 v164, v164
	v_rcp_f32_e32 v165, v165
	v_pk_mul_f32 v[12:13], v[12:13], v[156:157] op_sel_hi:[1,0]
	v_pk_mul_f32 v[14:15], v[14:15], v[156:157] op_sel_hi:[1,0]
	v_pk_mul_f32 v[8:9], v[8:9], v[156:157] op_sel_hi:[1,0]
	v_pk_mul_f32 v[10:11], v[10:11], v[156:157] op_sel_hi:[1,0]
	v_pk_mul_f32 v[12:13], v[12:13], v[158:159]
	v_pk_mul_f32 v[14:15], v[14:15], v[160:161]
	v_pk_mul_f32 v[8:9], v[8:9], v[162:163]
	v_pk_mul_f32 v[10:11], v[10:11], v[164:165]
	v_cvt_pk_bf16_f32 v4, v12, v13
	v_cvt_pk_bf16_f32 v5, v14, v15
	v_cvt_pk_bf16_f32 v6, v8, v9
	v_cvt_pk_bf16_f32 v7, v10, v11
	s_mov_b32 s22, 0xf2000
	v_lshl_add_u64 v[0:1], v[152:153], 0, s[22:23]
	global_store_dwordx4 v[0:1], v[4:7], off

.LBB0_1322:
	s_lshl_b32 s40, s20, 7
	s_ashr_i32 s41, s40, 31
	s_lshl_b64 s[40:41], s[40:41], 1
	v_mov_b64_e32 v[150:151], s[66:67]
	v_mad_i64_i32 v[152:153], s[50:51], v148, s36, v[150:151]
	v_lshl_add_u64 v[152:153], v[152:153], 0, s[40:41]
	v_and_b32_e32 v150, 0xf0, v136
	v_mov_b32_e32 v151, 0
	v_lshl_add_u64 v[152:153], v[152:153], 0, v[150:151]
	s_mov_b32 s51, 0
	v_mul_f32_e32 v154, 0xbfb8aa3b, v236
	v_mul_f32_e32 v156, v236, v236
	v_pk_mul_f32 v[158:159], v[116:117], v[154:155] op_sel_hi:[1,0]
	v_pk_mul_f32 v[160:161], v[118:119], v[154:155] op_sel_hi:[1,0]
	v_pk_mul_f32 v[162:163], v[112:113], v[154:155] op_sel_hi:[1,0]
	v_pk_mul_f32 v[164:165], v[114:115], v[154:155] op_sel_hi:[1,0]
	v_exp_f32_e32 v158, v158
	v_exp_f32_e32 v159, v159
	v_exp_f32_e32 v160, v160
	v_exp_f32_e32 v161, v161
	v_exp_f32_e32 v162, v162
	v_exp_f32_e32 v163, v163
	v_exp_f32_e32 v164, v164
	v_exp_f32_e32 v165, v165
	v_pk_mul_f32 v[124:125], v[116:117], v[124:125]
	v_pk_mul_f32 v[126:127], v[118:119], v[126:127]
	v_pk_mul_f32 v[120:121], v[112:113], v[120:121]
	v_pk_mul_f32 v[122:123], v[114:115], v[122:123]
	v_pk_add_f32 v[158:159], v[158:159], 1.0 op_sel_hi:[1,0]
	v_pk_add_f32 v[160:161], v[160:161], 1.0 op_sel_hi:[1,0]
	v_pk_add_f32 v[162:163], v[162:163], 1.0 op_sel_hi:[1,0]
	v_pk_add_f32 v[164:165], v[164:165], 1.0 op_sel_hi:[1,0]
	v_rcp_f32_e32 v158, v158
	v_rcp_f32_e32 v159, v159
	v_rcp_f32_e32 v160, v160
	v_rcp_f32_e32 v161, v161
	v_rcp_f32_e32 v162, v162
	v_rcp_f32_e32 v163, v163
	v_rcp_f32_e32 v164, v164
	v_rcp_f32_e32 v165, v165
	v_pk_mul_f32 v[124:125], v[124:125], v[156:157] op_sel_hi:[1,0]
	v_pk_mul_f32 v[126:127], v[126:127], v[156:157] op_sel_hi:[1,0]
	v_pk_mul_f32 v[120:121], v[120:121], v[156:157] op_sel_hi:[1,0]
	v_pk_mul_f32 v[122:123], v[122:123], v[156:157] op_sel_hi:[1,0]
	v_pk_mul_f32 v[124:125], v[124:125], v[158:159]
	v_pk_mul_f32 v[126:127], v[126:127], v[160:161]
	v_pk_mul_f32 v[120:121], v[120:121], v[162:163]
	v_pk_mul_f32 v[122:123], v[122:123], v[164:165]
	v_cvt_pk_bf16_f32 v116, v124, v125
	v_cvt_pk_bf16_f32 v117, v126, v127
	v_cvt_pk_bf16_f32 v118, v120, v121
	v_cvt_pk_bf16_f32 v119, v122, v123
	global_store_dwordx4 v[152:153], v[116:119], off
	v_mul_f32_e32 v154, 0xbfb8aa3b, v237
	v_mul_f32_e32 v156, v237, v237
	v_pk_mul_f32 v[158:159], v[100:101], v[154:155] op_sel_hi:[1,0]
	v_pk_mul_f32 v[160:161], v[102:103], v[154:155] op_sel_hi:[1,0]
	v_pk_mul_f32 v[162:163], v[96:97], v[154:155] op_sel_hi:[1,0]
	v_pk_mul_f32 v[164:165], v[98:99], v[154:155] op_sel_hi:[1,0]
	v_exp_f32_e32 v158, v158
	v_exp_f32_e32 v159, v159
	v_exp_f32_e32 v160, v160
	v_exp_f32_e32 v161, v161
	v_exp_f32_e32 v162, v162
	v_exp_f32_e32 v163, v163
	v_exp_f32_e32 v164, v164
	v_exp_f32_e32 v165, v165
	v_pk_mul_f32 v[108:109], v[100:101], v[108:109]
	v_pk_mul_f32 v[110:111], v[102:103], v[110:111]
	v_pk_mul_f32 v[104:105], v[96:97], v[104:105]
	v_pk_mul_f32 v[106:107], v[98:99], v[106:107]
	v_pk_add_f32 v[158:159], v[158:159], 1.0 op_sel_hi:[1,0]
	v_pk_add_f32 v[160:161], v[160:161], 1.0 op_sel_hi:[1,0]
	v_pk_add_f32 v[162:163], v[162:163], 1.0 op_sel_hi:[1,0]
	v_pk_add_f32 v[164:165], v[164:165], 1.0 op_sel_hi:[1,0]
	v_rcp_f32_e32 v158, v158
	v_rcp_f32_e32 v159, v159
	v_rcp_f32_e32 v160, v160
	v_rcp_f32_e32 v161, v161
	v_rcp_f32_e32 v162, v162
	v_rcp_f32_e32 v163, v163
	v_rcp_f32_e32 v164, v164
	v_rcp_f32_e32 v165, v165
	v_pk_mul_f32 v[108:109], v[108:109], v[156:157] op_sel_hi:[1,0]
	v_pk_mul_f32 v[110:111], v[110:111], v[156:157] op_sel_hi:[1,0]
	v_pk_mul_f32 v[104:105], v[104:105], v[156:157] op_sel_hi:[1,0]
	v_pk_mul_f32 v[106:107], v[106:107], v[156:157] op_sel_hi:[1,0]
	v_pk_mul_f32 v[108:109], v[108:109], v[158:159]
	v_pk_mul_f32 v[110:111], v[110:111], v[160:161]
	v_pk_mul_f32 v[104:105], v[104:105], v[162:163]
	v_pk_mul_f32 v[106:107], v[106:107], v[164:165]
	v_cvt_pk_bf16_f32 v100, v108, v109
	v_cvt_pk_bf16_f32 v101, v110, v111
	v_cvt_pk_bf16_f32 v102, v104, v105
	v_cvt_pk_bf16_f32 v103, v106, v107
	s_mov_b32 s50, 0x16000
	v_lshl_add_u64 v[96:97], v[152:153], 0, s[50:51]
	global_store_dwordx4 v[96:97], v[100:103], off
	v_mul_f32_e32 v154, 0xbfb8aa3b, v238
	v_mul_f32_e32 v156, v238, v238
	v_pk_mul_f32 v[158:159], v[84:85], v[154:155] op_sel_hi:[1,0]
	v_pk_mul_f32 v[160:161], v[86:87], v[154:155] op_sel_hi:[1,0]
	v_pk_mul_f32 v[162:163], v[80:81], v[154:155] op_sel_hi:[1,0]
	v_pk_mul_f32 v[164:165], v[82:83], v[154:155] op_sel_hi:[1,0]
	v_exp_f32_e32 v158, v158
	v_exp_f32_e32 v159, v159
	v_exp_f32_e32 v160, v160
	v_exp_f32_e32 v161, v161
	v_exp_f32_e32 v162, v162
	v_exp_f32_e32 v163, v163
	v_exp_f32_e32 v164, v164
	v_exp_f32_e32 v165, v165
	v_pk_mul_f32 v[92:93], v[84:85], v[92:93]
	v_pk_mul_f32 v[94:95], v[86:87], v[94:95]
	v_pk_mul_f32 v[88:89], v[80:81], v[88:89]
	v_pk_mul_f32 v[90:91], v[82:83], v[90:91]
	v_pk_add_f32 v[158:159], v[158:159], 1.0 op_sel_hi:[1,0]
	v_pk_add_f32 v[160:161], v[160:161], 1.0 op_sel_hi:[1,0]
	v_pk_add_f32 v[162:163], v[162:163], 1.0 op_sel_hi:[1,0]
	v_pk_add_f32 v[164:165], v[164:165], 1.0 op_sel_hi:[1,0]
	v_rcp_f32_e32 v158, v158
	v_rcp_f32_e32 v159, v159
	v_rcp_f32_e32 v160, v160
	v_rcp_f32_e32 v161, v161
	v_rcp_f32_e32 v162, v162
	v_rcp_f32_e32 v163, v163
	v_rcp_f32_e32 v164, v164
	v_rcp_f32_e32 v165, v165
	v_pk_mul_f32 v[92:93], v[92:93], v[156:157] op_sel_hi:[1,0]
	v_pk_mul_f32 v[94:95], v[94:95], v[156:157] op_sel_hi:[1,0]
	v_pk_mul_f32 v[88:89], v[88:89], v[156:157] op_sel_hi:[1,0]
	v_pk_mul_f32 v[90:91], v[90:91], v[156:157] op_sel_hi:[1,0]
	v_pk_mul_f32 v[92:93], v[92:93], v[158:159]
	v_pk_mul_f32 v[94:95], v[94:95], v[160:161]
	v_pk_mul_f32 v[88:89], v[88:89], v[162:163]
	v_pk_mul_f32 v[90:91], v[90:91], v[164:165]
	v_cvt_pk_bf16_f32 v84, v92, v93
	v_cvt_pk_bf16_f32 v85, v94, v95
	v_cvt_pk_bf16_f32 v86, v88, v89
	v_cvt_pk_bf16_f32 v87, v90, v91
	s_mov_b32 s50, 0x2c000
	v_lshl_add_u64 v[80:81], v[152:153], 0, s[50:51]
	global_store_dwordx4 v[80:81], v[84:87], off
	v_mul_f32_e32 v154, 0xbfb8aa3b, v239
	v_mul_f32_e32 v156, v239, v239
	v_pk_mul_f32 v[158:159], v[68:69], v[154:155] op_sel_hi:[1,0]
	v_pk_mul_f32 v[160:161], v[70:71], v[154:155] op_sel_hi:[1,0]
	v_pk_mul_f32 v[162:163], v[64:65], v[154:155] op_sel_hi:[1,0]
	v_pk_mul_f32 v[164:165], v[66:67], v[154:155] op_sel_hi:[1,0]
	v_exp_f32_e32 v158, v158
	v_exp_f32_e32 v159, v159
	v_exp_f32_e32 v160, v160
	v_exp_f32_e32 v161, v161
	v_exp_f32_e32 v162, v162
	v_exp_f32_e32 v163, v163
	v_exp_f32_e32 v164, v164
	v_exp_f32_e32 v165, v165
	v_pk_mul_f32 v[76:77], v[68:69], v[76:77]
	v_pk_mul_f32 v[78:79], v[70:71], v[78:79]
	v_pk_mul_f32 v[72:73], v[64:65], v[72:73]
	v_pk_mul_f32 v[74:75], v[66:67], v[74:75]
	v_pk_add_f32 v[158:159], v[158:159], 1.0 op_sel_hi:[1,0]
	v_pk_add_f32 v[160:161], v[160:161], 1.0 op_sel_hi:[1,0]
	v_pk_add_f32 v[162:163], v[162:163], 1.0 op_sel_hi:[1,0]
	v_pk_add_f32 v[164:165], v[164:165], 1.0 op_sel_hi:[1,0]
	v_rcp_f32_e32 v158, v158
	v_rcp_f32_e32 v159, v159
	v_rcp_f32_e32 v160, v160
	v_rcp_f32_e32 v161, v161
	v_rcp_f32_e32 v162, v162
	v_rcp_f32_e32 v163, v163
	v_rcp_f32_e32 v164, v164
	v_rcp_f32_e32 v165, v165
	v_pk_mul_f32 v[76:77], v[76:77], v[156:157] op_sel_hi:[1,0]
	v_pk_mul_f32 v[78:79], v[78:79], v[156:157] op_sel_hi:[1,0]
	v_pk_mul_f32 v[72:73], v[72:73], v[156:157] op_sel_hi:[1,0]
	v_pk_mul_f32 v[74:75], v[74:75], v[156:157] op_sel_hi:[1,0]
	v_pk_mul_f32 v[76:77], v[76:77], v[158:159]
	v_pk_mul_f32 v[78:79], v[78:79], v[160:161]
	v_pk_mul_f32 v[72:73], v[72:73], v[162:163]
	v_pk_mul_f32 v[74:75], v[74:75], v[164:165]
	v_cvt_pk_bf16_f32 v68, v76, v77
	v_cvt_pk_bf16_f32 v69, v78, v79
	v_cvt_pk_bf16_f32 v70, v72, v73
	v_cvt_pk_bf16_f32 v71, v74, v75
	s_mov_b32 s50, 0x42000
	v_lshl_add_u64 v[64:65], v[152:153], 0, s[50:51]
	global_store_dwordx4 v[64:65], v[68:71], off
	v_mul_f32_e32 v154, 0xbfb8aa3b, v240
	v_mul_f32_e32 v156, v240, v240
	v_pk_mul_f32 v[158:159], v[52:53], v[154:155] op_sel_hi:[1,0]
	v_pk_mul_f32 v[160:161], v[54:55], v[154:155] op_sel_hi:[1,0]
	v_pk_mul_f32 v[162:163], v[48:49], v[154:155] op_sel_hi:[1,0]
	v_pk_mul_f32 v[164:165], v[50:51], v[154:155] op_sel_hi:[1,0]
	v_exp_f32_e32 v158, v158
	v_exp_f32_e32 v159, v159
	v_exp_f32_e32 v160, v160
	v_exp_f32_e32 v161, v161
	v_exp_f32_e32 v162, v162
	v_exp_f32_e32 v163, v163
	v_exp_f32_e32 v164, v164
	v_exp_f32_e32 v165, v165
	v_pk_mul_f32 v[60:61], v[52:53], v[60:61]
	v_pk_mul_f32 v[62:63], v[54:55], v[62:63]
	v_pk_mul_f32 v[56:57], v[48:49], v[56:57]
	v_pk_mul_f32 v[58:59], v[50:51], v[58:59]
	v_pk_add_f32 v[158:159], v[158:159], 1.0 op_sel_hi:[1,0]
	v_pk_add_f32 v[160:161], v[160:161], 1.0 op_sel_hi:[1,0]
	v_pk_add_f32 v[162:163], v[162:163], 1.0 op_sel_hi:[1,0]
	v_pk_add_f32 v[164:165], v[164:165], 1.0 op_sel_hi:[1,0]
	v_rcp_f32_e32 v158, v158
	v_rcp_f32_e32 v159, v159
	v_rcp_f32_e32 v160, v160
	v_rcp_f32_e32 v161, v161
	v_rcp_f32_e32 v162, v162
	v_rcp_f32_e32 v163, v163
	v_rcp_f32_e32 v164, v164
	v_rcp_f32_e32 v165, v165
	v_pk_mul_f32 v[60:61], v[60:61], v[156:157] op_sel_hi:[1,0]
	v_pk_mul_f32 v[62:63], v[62:63], v[156:157] op_sel_hi:[1,0]
	v_pk_mul_f32 v[56:57], v[56:57], v[156:157] op_sel_hi:[1,0]
	v_pk_mul_f32 v[58:59], v[58:59], v[156:157] op_sel_hi:[1,0]
	v_pk_mul_f32 v[60:61], v[60:61], v[158:159]
	v_pk_mul_f32 v[62:63], v[62:63], v[160:161]
	v_pk_mul_f32 v[56:57], v[56:57], v[162:163]
	v_pk_mul_f32 v[58:59], v[58:59], v[164:165]
	v_cvt_pk_bf16_f32 v52, v60, v61
	v_cvt_pk_bf16_f32 v53, v62, v63
	v_cvt_pk_bf16_f32 v54, v56, v57
	v_cvt_pk_bf16_f32 v55, v58, v59
	s_mov_b32 s50, 0xb0000
	v_lshl_add_u64 v[48:49], v[152:153], 0, s[50:51]
	global_store_dwordx4 v[48:49], v[52:55], off
	v_mul_f32_e32 v154, 0xbfb8aa3b, v241
	v_mul_f32_e32 v156, v241, v241
	v_pk_mul_f32 v[158:159], v[36:37], v[154:155] op_sel_hi:[1,0]
	v_pk_mul_f32 v[160:161], v[38:39], v[154:155] op_sel_hi:[1,0]
	v_pk_mul_f32 v[162:163], v[32:33], v[154:155] op_sel_hi:[1,0]
	v_pk_mul_f32 v[164:165], v[34:35], v[154:155] op_sel_hi:[1,0]
	v_exp_f32_e32 v158, v158
	v_exp_f32_e32 v159, v159
	v_exp_f32_e32 v160, v160
	v_exp_f32_e32 v161, v161
	v_exp_f32_e32 v162, v162
	v_exp_f32_e32 v163, v163
	v_exp_f32_e32 v164, v164
	v_exp_f32_e32 v165, v165
	v_pk_mul_f32 v[44:45], v[36:37], v[44:45]
	v_pk_mul_f32 v[46:47], v[38:39], v[46:47]
	v_pk_mul_f32 v[40:41], v[32:33], v[40:41]
	v_pk_mul_f32 v[42:43], v[34:35], v[42:43]
	v_pk_add_f32 v[158:159], v[158:159], 1.0 op_sel_hi:[1,0]
	v_pk_add_f32 v[160:161], v[160:161], 1.0 op_sel_hi:[1,0]
	v_pk_add_f32 v[162:163], v[162:163], 1.0 op_sel_hi:[1,0]
	v_pk_add_f32 v[164:165], v[164:165], 1.0 op_sel_hi:[1,0]
	v_rcp_f32_e32 v158, v158
	v_rcp_f32_e32 v159, v159
	v_rcp_f32_e32 v160, v160
	v_rcp_f32_e32 v161, v161
	v_rcp_f32_e32 v162, v162
	v_rcp_f32_e32 v163, v163
	v_rcp_f32_e32 v164, v164
	v_rcp_f32_e32 v165, v165
	v_pk_mul_f32 v[44:45], v[44:45], v[156:157] op_sel_hi:[1,0]
	v_pk_mul_f32 v[46:47], v[46:47], v[156:157] op_sel_hi:[1,0]
	v_pk_mul_f32 v[40:41], v[40:41], v[156:157] op_sel_hi:[1,0]
	v_pk_mul_f32 v[42:43], v[42:43], v[156:157] op_sel_hi:[1,0]
	v_pk_mul_f32 v[44:45], v[44:45], v[158:159]
	v_pk_mul_f32 v[46:47], v[46:47], v[160:161]
	v_pk_mul_f32 v[40:41], v[40:41], v[162:163]
	v_pk_mul_f32 v[42:43], v[42:43], v[164:165]
	v_cvt_pk_bf16_f32 v36, v44, v45
	v_cvt_pk_bf16_f32 v37, v46, v47
	v_cvt_pk_bf16_f32 v38, v40, v41
	v_cvt_pk_bf16_f32 v39, v42, v43
	s_mov_b32 s50, 0xc6000
	v_lshl_add_u64 v[32:33], v[152:153], 0, s[50:51]
	global_store_dwordx4 v[32:33], v[36:39], off
	v_mul_f32_e32 v154, 0xbfb8aa3b, v242
	v_mul_f32_e32 v156, v242, v242
	v_pk_mul_f32 v[158:159], v[20:21], v[154:155] op_sel_hi:[1,0]
	v_pk_mul_f32 v[160:161], v[22:23], v[154:155] op_sel_hi:[1,0]
	v_pk_mul_f32 v[162:163], v[16:17], v[154:155] op_sel_hi:[1,0]
	v_pk_mul_f32 v[164:165], v[18:19], v[154:155] op_sel_hi:[1,0]
	v_exp_f32_e32 v158, v158
	v_exp_f32_e32 v159, v159
	v_exp_f32_e32 v160, v160
	v_exp_f32_e32 v161, v161
	v_exp_f32_e32 v162, v162
	v_exp_f32_e32 v163, v163
	v_exp_f32_e32 v164, v164
	v_exp_f32_e32 v165, v165
	v_pk_mul_f32 v[28:29], v[20:21], v[28:29]
	v_pk_mul_f32 v[30:31], v[22:23], v[30:31]
	v_pk_mul_f32 v[24:25], v[16:17], v[24:25]
	v_pk_mul_f32 v[26:27], v[18:19], v[26:27]
	v_pk_add_f32 v[158:159], v[158:159], 1.0 op_sel_hi:[1,0]
	v_pk_add_f32 v[160:161], v[160:161], 1.0 op_sel_hi:[1,0]
	v_pk_add_f32 v[162:163], v[162:163], 1.0 op_sel_hi:[1,0]
	v_pk_add_f32 v[164:165], v[164:165], 1.0 op_sel_hi:[1,0]
	v_rcp_f32_e32 v158, v158
	v_rcp_f32_e32 v159, v159
	v_rcp_f32_e32 v160, v160
	v_rcp_f32_e32 v161, v161
	v_rcp_f32_e32 v162, v162
	v_rcp_f32_e32 v163, v163
	v_rcp_f32_e32 v164, v164
	v_rcp_f32_e32 v165, v165
	v_pk_mul_f32 v[28:29], v[28:29], v[156:157] op_sel_hi:[1,0]
	v_pk_mul_f32 v[30:31], v[30:31], v[156:157] op_sel_hi:[1,0]
	v_pk_mul_f32 v[24:25], v[24:25], v[156:157] op_sel_hi:[1,0]
	v_pk_mul_f32 v[26:27], v[26:27], v[156:157] op_sel_hi:[1,0]
	v_pk_mul_f32 v[28:29], v[28:29], v[158:159]
	v_pk_mul_f32 v[30:31], v[30:31], v[160:161]
	v_pk_mul_f32 v[24:25], v[24:25], v[162:163]
	v_pk_mul_f32 v[26:27], v[26:27], v[164:165]
	v_cvt_pk_bf16_f32 v20, v28, v29
	v_cvt_pk_bf16_f32 v21, v30, v31
	v_cvt_pk_bf16_f32 v22, v24, v25
	v_cvt_pk_bf16_f32 v23, v26, v27
	s_mov_b32 s50, 0xdc000
	v_lshl_add_u64 v[16:17], v[152:153], 0, s[50:51]
	global_store_dwordx4 v[16:17], v[20:23], off
	v_mul_f32_e32 v154, 0xbfb8aa3b, v243
	v_mul_f32_e32 v156, v243, v243
	v_pk_mul_f32 v[158:159], v[4:5], v[154:155] op_sel_hi:[1,0]
	v_pk_mul_f32 v[160:161], v[6:7], v[154:155] op_sel_hi:[1,0]
	v_pk_mul_f32 v[162:163], v[0:1], v[154:155] op_sel_hi:[1,0]
	v_pk_mul_f32 v[164:165], v[2:3], v[154:155] op_sel_hi:[1,0]
	v_exp_f32_e32 v158, v158
	v_exp_f32_e32 v159, v159
	v_exp_f32_e32 v160, v160
	v_exp_f32_e32 v161, v161
	v_exp_f32_e32 v162, v162
	v_exp_f32_e32 v163, v163
	v_exp_f32_e32 v164, v164
	v_exp_f32_e32 v165, v165
	v_pk_mul_f32 v[12:13], v[4:5], v[12:13]
	v_pk_mul_f32 v[14:15], v[6:7], v[14:15]
	v_pk_mul_f32 v[8:9], v[0:1], v[8:9]
	v_pk_mul_f32 v[10:11], v[2:3], v[10:11]
	v_pk_add_f32 v[158:159], v[158:159], 1.0 op_sel_hi:[1,0]
	v_pk_add_f32 v[160:161], v[160:161], 1.0 op_sel_hi:[1,0]
	v_pk_add_f32 v[162:163], v[162:163], 1.0 op_sel_hi:[1,0]
	v_pk_add_f32 v[164:165], v[164:165], 1.0 op_sel_hi:[1,0]
	v_rcp_f32_e32 v158, v158
	v_rcp_f32_e32 v159, v159
	v_rcp_f32_e32 v160, v160
	v_rcp_f32_e32 v161, v161
	v_rcp_f32_e32 v162, v162
	v_rcp_f32_e32 v163, v163
	v_rcp_f32_e32 v164, v164
	v_rcp_f32_e32 v165, v165
	v_pk_mul_f32 v[12:13], v[12:13], v[156:157] op_sel_hi:[1,0]
	v_pk_mul_f32 v[14:15], v[14:15], v[156:157] op_sel_hi:[1,0]
	v_pk_mul_f32 v[8:9], v[8:9], v[156:157] op_sel_hi:[1,0]
	v_pk_mul_f32 v[10:11], v[10:11], v[156:157] op_sel_hi:[1,0]
	v_pk_mul_f32 v[12:13], v[12:13], v[158:159]
	v_pk_mul_f32 v[14:15], v[14:15], v[160:161]
	v_pk_mul_f32 v[8:9], v[8:9], v[162:163]
	v_pk_mul_f32 v[10:11], v[10:11], v[164:165]
	v_cvt_pk_bf16_f32 v4, v12, v13
	v_cvt_pk_bf16_f32 v5, v14, v15
	v_cvt_pk_bf16_f32 v6, v8, v9
	v_cvt_pk_bf16_f32 v7, v10, v11
	s_mov_b32 s50, 0xf2000
	v_lshl_add_u64 v[0:1], v[152:153], 0, s[50:51]
	global_store_dwordx4 v[0:1], v[4:7], off
	s_mov_b64 s[40:41], 0
